# D tile loop: packed subtract and packed row-sum tree in the softmax block (16 fewer VALU per tile), exps and bf16 packing in place
# baseline (speedup 1.0000x reference)
; DI unsigned cvtpk(float lo, float hi) { f32x2_t v = {lo, hi}; bf16x2_t b = __builtin_convertvector(v, bf16x2_t); return __builtin_bit_cast(unsigned, b); }
; DI float fexp2(float x) { return __builtin_amdgcn_exp2f(x); }
; DI float half_sum(float v) { auto rr = __builtin_amdgcn_permlane32_swap(__float_as_uint(v), __float_as_uint(v), false, false); return __uint_as_float(rr[0]) + __uint_as_float(rr[1]); }
; #define MFMA32(a, b, c) __builtin_amdgcn_mfma_f32_32x32x16_bf16((a), (b), (c), 0, 0, 0)
; template <bool MASKED>
; DI void attn_tile_sw(int MODE, LAS const unsigned char* kst, LAS const unsigned char* vst, const bf16x8 (&qf)[4], float bstep, float ca, int lane, f32x16& o0, f32x16& o1, float& m, float& l) {
;     ...
;     float ps = 0.f;
; #pragma unroll
;     for (int r = 0; r < 16; ++r) { s[r] = fexp2(s[r] - mrel); ps += s[r]; }
;     l += half_sum(ps);
;     v4u pa, pb;
;     pa.x = cvtpk(s[0], s[1]); pa.y = cvtpk(s[2], s[3]); pa.z = cvtpk(s[4], s[5]); pa.w = cvtpk(s[6], s[7]);
;     pb.x = cvtpk(s[8], s[9]); pb.y = cvtpk(s[10], s[11]); pb.z = cvtpk(s[12], s[13]); pb.w = cvtpk(s[14], s[15]);
;     const bf16x8 p0 = __builtin_bit_cast(bf16x8, pa), p1 = __builtin_bit_cast(bf16x8, pb);
;     o0 = MFMA32(__builtin_shufflevector(va0, va1, 0, 1, 2, 3, 4, 5, 6, 7), p0, o0);
;     o1 = MFMA32(__builtin_shufflevector(vb0, vb1, 0, 1, 2, 3, 4, 5, 6, 7), p0, o1);
;     o0 = MFMA32(__builtin_shufflevector(vc0, vc1, 0, 1, 2, 3, 4, 5, 6, 7), p1, o0);
;     o1 = MFMA32(__builtin_shufflevector(vd0, vd1, 0, 1, 2, 3, 4, 5, 6, 7), p1, o1);
.Ldil_norescale:
	v_sub_f32_e32 v243, v17, v3
	v_mov_b32_e32 v198, v17
	v_pk_add_f32 v[98:99], v[98:99], v[242:243] op_sel:[0,1] op_sel_hi:[1,1] neg_lo:[0,1] neg_hi:[0,1]
	v_pk_add_f32 v[100:101], v[100:101], v[242:243] op_sel:[0,1] op_sel_hi:[1,1] neg_lo:[0,1] neg_hi:[0,1]
	v_pk_add_f32 v[102:103], v[102:103], v[242:243] op_sel:[0,1] op_sel_hi:[1,1] neg_lo:[0,1] neg_hi:[0,1]
	v_pk_add_f32 v[104:105], v[104:105], v[242:243] op_sel:[0,1] op_sel_hi:[1,1] neg_lo:[0,1] neg_hi:[0,1]
	v_pk_add_f32 v[106:107], v[106:107], v[242:243] op_sel:[0,1] op_sel_hi:[1,1] neg_lo:[0,1] neg_hi:[0,1]
	v_pk_add_f32 v[108:109], v[108:109], v[242:243] op_sel:[0,1] op_sel_hi:[1,1] neg_lo:[0,1] neg_hi:[0,1]
	v_pk_add_f32 v[110:111], v[110:111], v[242:243] op_sel:[0,1] op_sel_hi:[1,1] neg_lo:[0,1] neg_hi:[0,1]
	v_pk_add_f32 v[112:113], v[112:113], v[242:243] op_sel:[0,1] op_sel_hi:[1,1] neg_lo:[0,1] neg_hi:[0,1]
	v_exp_f32_e32 v98, v98
	v_exp_f32_e32 v99, v99
	v_exp_f32_e32 v100, v100
	v_exp_f32_e32 v101, v101
	v_exp_f32_e32 v102, v102
	v_exp_f32_e32 v103, v103
	v_exp_f32_e32 v104, v104
	v_exp_f32_e32 v105, v105
	v_exp_f32_e32 v106, v106
	v_exp_f32_e32 v107, v107
	v_exp_f32_e32 v108, v108
	v_exp_f32_e32 v109, v109
	v_exp_f32_e32 v110, v110
	v_exp_f32_e32 v111, v111
	v_exp_f32_e32 v112, v112
	v_exp_f32_e32 v113, v113
	v_pk_add_f32 v[244:245], v[98:99], v[100:101]
	v_pk_add_f32 v[244:245], v[244:245], v[102:103]
	v_pk_add_f32 v[244:245], v[244:245], v[104:105]
	v_pk_add_f32 v[244:245], v[244:245], v[106:107]
	v_pk_add_f32 v[244:245], v[244:245], v[108:109]
	v_pk_add_f32 v[244:245], v[244:245], v[110:111]
	v_pk_add_f32 v[244:245], v[244:245], v[112:113]
	v_cvt_pk_bf16_f32 v101, v100, v101
	v_cvt_pk_bf16_f32 v100, v98, v99
	v_add_f32_e32 v98, v244, v245
	v_cvt_pk_bf16_f32 v102, v102, v103
	v_cvt_pk_bf16_f32 v103, v104, v105
	v_mov_b32_e32 v99, v98
	v_cvt_pk_bf16_f32 v104, v106, v107
	v_cvt_pk_bf16_f32 v105, v108, v109
	v_permlane32_swap_b32_e32 v98, v99
	v_cvt_pk_bf16_f32 v106, v110, v111
	v_cvt_pk_bf16_f32 v107, v112, v113
	v_add_f32_e32 v98, v98, v99
	s_nop 0
	v_add_f32_e32 v185, v185, v98
	s_cbranch_scc1 .Ldil_pv0
	s_waitcnt lgkmcnt(6)
	v_mfma_f32_32x32x16_bf16 v[66:81], v[178:181], v[100:103], v[66:81]
	s_waitcnt lgkmcnt(2)
	v_mfma_f32_32x32x16_bf16 v[82:97], v[12:15], v[100:103], v[82:97]
	s_branch .Ldil_pv1
.Ldil_pv0:
	s_waitcnt lgkmcnt(6)
	v_mfma_f32_32x32x16_bf16 v[66:81], v[178:181], v[100:103], 0
	s_waitcnt lgkmcnt(2)
	v_mfma_f32_32x32x16_bf16 v[82:97], v[12:15], v[100:103], 0
